# P1 epilogue split into gate / non-gate paths with grouped nop-free sigmoid chains (on top of v8)
# speedup vs baseline: 1.0216x; 1.0009x over previous
; __device__ __forceinline__ u32x4 pack8(const float* f) { u32x4 w; w.x = cvt_pk_bf16(f[0], f[1]); w.y = cvt_pk_bf16(f[2], f[3]); w.z = cvt_pk_bf16(f[4], f[5]); w.w = cvt_pk_bf16(f[6], f[7]); return w; }
;     __device__ __forceinline__ void operator()(AccT& acc, const Unit& u, int wr, int wc, int fr, int fq) const {
;         const bool gate = u.pn >= 5;
;         const int col0 = u.pn * 256 + wc * 32 + 8 * fq;
;         f32x4 gb[2][2];
; #pragma unroll
;         for (int bj = 0; bj < 2; ++bj)
; #pragma unroll
;             for (int n = 0; n < 2; ++n) gb[bj][n] = gate ? *(const f32x4*)(gbias + (col0 - 1280) + bj * 128 + 4 * n) : (f32x4){0.f, 0.f, 0.f, 0.f};
;         float rsv[2][4];
; #pragma unroll
;         for (int ai = 0; ai < 2; ++ai)
; #pragma unroll
;             for (int m = 0; m < 4; ++m) rsv[ai][m] = ssq[u.pm * 256 + ai * 128 + wr * 64 + m * 16 + fr];
; #pragma unroll
;         for (int ai = 0; ai < 2; ++ai)
; #pragma unroll
;             for (int m = 0; m < 4; ++m) {
;                 const int row = u.pm * 256 + ai * 128 + wr * 64 + m * 16 + fr;
;                 const float rs = __builtin_amdgcn_rsqf(rsv[ai][m] * (1.0f / 1024.0f) + EPS);
;                 bf16_t* rowp = P + (size_t)row * INW + col0;
; #pragma unroll
;                 for (int bj = 0; bj < 2; ++bj) {
;                     float v[8];
; #pragma unroll
;                     for (int n = 0; n < 2; ++n)
; #pragma unroll
;                         for (int j = 0; j < 4; ++j) {
;                             float x = acc[ai][bj][m][n][j] * rs;
;                             if (gate) { x += gb[bj][n][j]; x = __builtin_amdgcn_rcpf(1.0f + __builtin_amdgcn_exp2f(-LOG2E * x)); }
;                             v[n * 4 + j] = x;
;                         }
;                     *(u32x4*)(rowp + bj * 128) = pack8(v);
;                 }
;             }
;     }
.LBB0_185:
	s_lshl_b32 s0, s49, 8
	s_add_i32 s0, s0, s33
	v_add_u32_e32 v160, s0, v160
	v_ashrrev_i32_e32 v161, 31, v160
	v_lshl_add_u64 v[156:157], v[160:161], 2, s[46:47]
	global_load_dword v161, v[156:157], off
	global_load_dword v179, v[156:157], off offset:64
	global_load_dword v177, v[156:157], off offset:128
	global_load_dword v175, v[156:157], off offset:192
	global_load_dword v173, v[156:157], off offset:512
	global_load_dword v171, v[156:157], off offset:576
	global_load_dword v169, v[156:157], off offset:640
	global_load_dword v167, v[156:157], off offset:704
	v_add_u32_e32 v178, 16, v160
	v_add_u32_e32 v176, 32, v160
	v_add_u32_e32 v174, 48, v160
	v_add_u32_e32 v172, 0x80, v160
	v_add_u32_e32 v170, 0x90, v160
	v_add_u32_e32 v168, 0xa0, v160
	v_add_u32_e32 v166, 0xb0, v160
	v_lshlrev_b64 v[158:159], 1, v[158:159]
	s_andn2_b64 vcc, exec, s[40:41]
	s_waitcnt vmcnt(0) lgkmcnt(0)
	s_cmp_eq_u64 s[42:43], 0
	s_cbranch_scc1 .Lmy_p1_nongate
	v_fmamk_f32 v156, v161, 0x3a800000, v223
	v_rsq_f32_e32 v180, v156
	v_mov_b64_e32 v[156:157], s[84:85]
	v_mad_i64_i32 v[160:161], s[0:1], v160, s89, v[156:157]
	v_lshl_add_u64 v[160:161], v[160:161], 0, v[158:159]
	v_fma_f32 v206, v142, v180, v52
	v_fma_f32 v207, v143, v180, v53
	v_fma_f32 v208, v144, v180, v54
	v_fma_f32 v209, v145, v180, v55
	v_fma_f32 v210, v138, v180, v44
	v_fma_f32 v211, v139, v180, v45
	v_fma_f32 v212, v140, v180, v46
	v_fma_f32 v213, v141, v180, v47
	v_mul_f32_e32 v206, 0xbfb8aa3b, v206
	v_mul_f32_e32 v207, 0xbfb8aa3b, v207
	v_mul_f32_e32 v208, 0xbfb8aa3b, v208
	v_mul_f32_e32 v209, 0xbfb8aa3b, v209
	v_mul_f32_e32 v210, 0xbfb8aa3b, v210
	v_mul_f32_e32 v211, 0xbfb8aa3b, v211
	v_mul_f32_e32 v212, 0xbfb8aa3b, v212
	v_mul_f32_e32 v213, 0xbfb8aa3b, v213
	v_exp_f32_e32 v206, v206
	v_exp_f32_e32 v207, v207
	v_exp_f32_e32 v208, v208
	v_exp_f32_e32 v209, v209
	v_exp_f32_e32 v210, v210
	v_exp_f32_e32 v211, v211
	v_exp_f32_e32 v212, v212
	v_exp_f32_e32 v213, v213
	v_add_f32_e32 v206, 1.0, v206
	v_add_f32_e32 v207, 1.0, v207
	v_add_f32_e32 v208, 1.0, v208
	v_add_f32_e32 v209, 1.0, v209
	v_add_f32_e32 v210, 1.0, v210
	v_add_f32_e32 v211, 1.0, v211
	v_add_f32_e32 v212, 1.0, v212
	v_add_f32_e32 v213, 1.0, v213
	v_rcp_f32_e32 v142, v206
	v_rcp_f32_e32 v143, v207
	v_rcp_f32_e32 v144, v208
	v_rcp_f32_e32 v145, v209
	v_rcp_f32_e32 v181, v210
	v_rcp_f32_e32 v182, v211
	v_rcp_f32_e32 v183, v212
	v_rcp_f32_e32 v141, v213
	v_cvt_pk_bf16_f32 v138, v142, v143
	v_cvt_pk_bf16_f32 v139, v144, v145
	v_cvt_pk_bf16_f32 v140, v181, v182
	v_cvt_pk_bf16_f32 v141, v183, v141
	global_store_dwordx4 v[160:161], v[138:141], off
	s_nop 1
	v_fma_f32 v206, v134, v180, v40
	v_fma_f32 v207, v135, v180, v41
	v_fma_f32 v208, v136, v180, v42
	v_fma_f32 v209, v137, v180, v43
	v_fma_f32 v210, v130, v180, v32
	v_fma_f32 v211, v131, v180, v33
	v_fma_f32 v212, v132, v180, v34
	v_fma_f32 v213, v133, v180, v35
	v_mul_f32_e32 v206, 0xbfb8aa3b, v206
	v_mul_f32_e32 v207, 0xbfb8aa3b, v207
	v_mul_f32_e32 v208, 0xbfb8aa3b, v208
	v_mul_f32_e32 v209, 0xbfb8aa3b, v209
	v_mul_f32_e32 v210, 0xbfb8aa3b, v210
	v_mul_f32_e32 v211, 0xbfb8aa3b, v211
	v_mul_f32_e32 v212, 0xbfb8aa3b, v212
	v_mul_f32_e32 v213, 0xbfb8aa3b, v213
	v_exp_f32_e32 v206, v206
	v_exp_f32_e32 v207, v207
	v_exp_f32_e32 v208, v208
	v_exp_f32_e32 v209, v209
	v_exp_f32_e32 v210, v210
	v_exp_f32_e32 v211, v211
	v_exp_f32_e32 v212, v212
	v_exp_f32_e32 v213, v213
	v_add_f32_e32 v206, 1.0, v206
	v_add_f32_e32 v207, 1.0, v207
	v_add_f32_e32 v208, 1.0, v208
	v_add_f32_e32 v209, 1.0, v209
	v_add_f32_e32 v210, 1.0, v210
	v_add_f32_e32 v211, 1.0, v211
	v_add_f32_e32 v212, 1.0, v212
	v_add_f32_e32 v213, 1.0, v213
	v_rcp_f32_e32 v134, v206
	v_rcp_f32_e32 v135, v207
	v_rcp_f32_e32 v136, v208
	v_rcp_f32_e32 v137, v209
	v_rcp_f32_e32 v138, v210
	v_rcp_f32_e32 v139, v211
	v_rcp_f32_e32 v140, v212
	v_rcp_f32_e32 v133, v213
	v_cvt_pk_bf16_f32 v130, v134, v135
	v_cvt_pk_bf16_f32 v131, v136, v137
	v_cvt_pk_bf16_f32 v132, v138, v139
	v_cvt_pk_bf16_f32 v133, v140, v133
	global_store_dwordx4 v[160:161], v[130:133], off offset:256
	s_nop 1
	v_fmamk_f32 v130, v179, 0x3a800000, v223
	v_rsq_f32_e32 v132, v130
	v_mad_i64_i32 v[130:131], s[0:1], v178, s89, v[156:157]
	v_lshl_add_u64 v[130:131], v[130:131], 0, v[158:159]
	v_fma_f32 v206, v126, v132, v52
	v_fma_f32 v207, v127, v132, v53
	v_fma_f32 v208, v128, v132, v54
	v_fma_f32 v209, v129, v132, v55
	v_fma_f32 v210, v122, v132, v44
	v_fma_f32 v211, v123, v132, v45
	v_fma_f32 v212, v124, v132, v46
	v_fma_f32 v213, v125, v132, v47
	v_mul_f32_e32 v206, 0xbfb8aa3b, v206
	v_mul_f32_e32 v207, 0xbfb8aa3b, v207
	v_mul_f32_e32 v208, 0xbfb8aa3b, v208
	v_mul_f32_e32 v209, 0xbfb8aa3b, v209
	v_mul_f32_e32 v210, 0xbfb8aa3b, v210
	v_mul_f32_e32 v211, 0xbfb8aa3b, v211
	v_mul_f32_e32 v212, 0xbfb8aa3b, v212
	v_mul_f32_e32 v213, 0xbfb8aa3b, v213
	v_exp_f32_e32 v206, v206
	v_exp_f32_e32 v207, v207
	v_exp_f32_e32 v208, v208
	v_exp_f32_e32 v209, v209
	v_exp_f32_e32 v210, v210
	v_exp_f32_e32 v211, v211
	v_exp_f32_e32 v212, v212
	v_exp_f32_e32 v213, v213
	v_add_f32_e32 v206, 1.0, v206
	v_add_f32_e32 v207, 1.0, v207
	v_add_f32_e32 v208, 1.0, v208
	v_add_f32_e32 v209, 1.0, v209
	v_add_f32_e32 v210, 1.0, v210
	v_add_f32_e32 v211, 1.0, v211
	v_add_f32_e32 v212, 1.0, v212
	v_add_f32_e32 v213, 1.0, v213
	v_rcp_f32_e32 v126, v206
	v_rcp_f32_e32 v127, v207
	v_rcp_f32_e32 v128, v208
	v_rcp_f32_e32 v129, v209
	v_rcp_f32_e32 v133, v210
	v_rcp_f32_e32 v134, v211
	v_rcp_f32_e32 v135, v212
	v_rcp_f32_e32 v125, v213
	v_cvt_pk_bf16_f32 v122, v126, v127
	v_cvt_pk_bf16_f32 v123, v128, v129
	v_cvt_pk_bf16_f32 v124, v133, v134
	v_cvt_pk_bf16_f32 v125, v135, v125
	global_store_dwordx4 v[130:131], v[122:125], off
; __device__ __forceinline__ u32x4 pack8(const float* f) { u32x4 w; w.x = cvt_pk_bf16(f[0], f[1]); w.y = cvt_pk_bf16(f[2], f[3]); w.z = cvt_pk_bf16(f[4], f[5]); w.w = cvt_pk_bf16(f[6], f[7]); return w; }
;     __device__ __forceinline__ void operator()(AccT& acc, const Unit& u, int wr, int wc, int fr, int fq) const {
;         const bool gate = u.pn >= 5;
;         const int col0 = u.pn * 256 + wc * 32 + 8 * fq;
;         f32x4 gb[2][2];
; #pragma unroll
;         for (int bj = 0; bj < 2; ++bj)
; #pragma unroll
;             for (int n = 0; n < 2; ++n) gb[bj][n] = gate ? *(const f32x4*)(gbias + (col0 - 1280) + bj * 128 + 4 * n) : (f32x4){0.f, 0.f, 0.f, 0.f};
;         float rsv[2][4];
; #pragma unroll
;         for (int ai = 0; ai < 2; ++ai)
; #pragma unroll
;             for (int m = 0; m < 4; ++m) rsv[ai][m] = ssq[u.pm * 256 + ai * 128 + wr * 64 + m * 16 + fr];
; #pragma unroll
;         for (int ai = 0; ai < 2; ++ai)
; #pragma unroll
;             for (int m = 0; m < 4; ++m) {
;                 const int row = u.pm * 256 + ai * 128 + wr * 64 + m * 16 + fr;
;                 const float rs = __builtin_amdgcn_rsqf(rsv[ai][m] * (1.0f / 1024.0f) + EPS);
;                 bf16_t* rowp = P + (size_t)row * INW + col0;
; #pragma unroll
;                 for (int bj = 0; bj < 2; ++bj) {
;                     float v[8];
; #pragma unroll
;                     for (int n = 0; n < 2; ++n)
; #pragma unroll
;                         for (int j = 0; j < 4; ++j) {
;                             float x = acc[ai][bj][m][n][j] * rs;
;                             if (gate) { x += gb[bj][n][j]; x = __builtin_amdgcn_rcpf(1.0f + __builtin_amdgcn_exp2f(-LOG2E * x)); }
;                             v[n * 4 + j] = x;
;                         }
;                     *(u32x4*)(rowp + bj * 128) = pack8(v);
;                 }
;             }
;     }
	s_nop 1
	v_fma_f32 v206, v118, v132, v40
	v_fma_f32 v207, v119, v132, v41
	v_fma_f32 v208, v120, v132, v42
	v_fma_f32 v209, v121, v132, v43
	v_fma_f32 v210, v114, v132, v32
	v_fma_f32 v211, v115, v132, v33
	v_fma_f32 v212, v116, v132, v34
	v_fma_f32 v213, v117, v132, v35
	v_mul_f32_e32 v206, 0xbfb8aa3b, v206
	v_mul_f32_e32 v207, 0xbfb8aa3b, v207
	v_mul_f32_e32 v208, 0xbfb8aa3b, v208
	v_mul_f32_e32 v209, 0xbfb8aa3b, v209
	v_mul_f32_e32 v210, 0xbfb8aa3b, v210
	v_mul_f32_e32 v211, 0xbfb8aa3b, v211
	v_mul_f32_e32 v212, 0xbfb8aa3b, v212
	v_mul_f32_e32 v213, 0xbfb8aa3b, v213
	v_exp_f32_e32 v206, v206
	v_exp_f32_e32 v207, v207
	v_exp_f32_e32 v208, v208
	v_exp_f32_e32 v209, v209
	v_exp_f32_e32 v210, v210
	v_exp_f32_e32 v211, v211
	v_exp_f32_e32 v212, v212
	v_exp_f32_e32 v213, v213
	v_add_f32_e32 v206, 1.0, v206
	v_add_f32_e32 v207, 1.0, v207
	v_add_f32_e32 v208, 1.0, v208
	v_add_f32_e32 v209, 1.0, v209
	v_add_f32_e32 v210, 1.0, v210
	v_add_f32_e32 v211, 1.0, v211
	v_add_f32_e32 v212, 1.0, v212
	v_add_f32_e32 v213, 1.0, v213
	v_rcp_f32_e32 v118, v206
	v_rcp_f32_e32 v119, v207
	v_rcp_f32_e32 v120, v208
	v_rcp_f32_e32 v121, v209
	v_rcp_f32_e32 v122, v210
	v_rcp_f32_e32 v123, v211
	v_rcp_f32_e32 v124, v212
	v_rcp_f32_e32 v117, v213
	v_cvt_pk_bf16_f32 v114, v118, v119
	v_cvt_pk_bf16_f32 v115, v120, v121
	v_cvt_pk_bf16_f32 v116, v122, v123
	v_cvt_pk_bf16_f32 v117, v124, v117
	global_store_dwordx4 v[130:131], v[114:117], off offset:256
	s_nop 1
	v_fmamk_f32 v114, v177, 0x3a800000, v223
	v_rsq_f32_e32 v116, v114
	v_mad_i64_i32 v[114:115], s[0:1], v176, s89, v[156:157]
	v_lshl_add_u64 v[114:115], v[114:115], 0, v[158:159]
	v_fma_f32 v206, v110, v116, v52
	v_fma_f32 v207, v111, v116, v53
	v_fma_f32 v208, v112, v116, v54
	v_fma_f32 v209, v113, v116, v55
	v_fma_f32 v210, v106, v116, v44
	v_fma_f32 v211, v107, v116, v45
	v_fma_f32 v212, v108, v116, v46
	v_fma_f32 v213, v109, v116, v47
	v_mul_f32_e32 v206, 0xbfb8aa3b, v206
	v_mul_f32_e32 v207, 0xbfb8aa3b, v207
	v_mul_f32_e32 v208, 0xbfb8aa3b, v208
	v_mul_f32_e32 v209, 0xbfb8aa3b, v209
	v_mul_f32_e32 v210, 0xbfb8aa3b, v210
	v_mul_f32_e32 v211, 0xbfb8aa3b, v211
	v_mul_f32_e32 v212, 0xbfb8aa3b, v212
	v_mul_f32_e32 v213, 0xbfb8aa3b, v213
	v_exp_f32_e32 v206, v206
	v_exp_f32_e32 v207, v207
	v_exp_f32_e32 v208, v208
	v_exp_f32_e32 v209, v209
	v_exp_f32_e32 v210, v210
	v_exp_f32_e32 v211, v211
	v_exp_f32_e32 v212, v212
	v_exp_f32_e32 v213, v213
	v_add_f32_e32 v206, 1.0, v206
	v_add_f32_e32 v207, 1.0, v207
	v_add_f32_e32 v208, 1.0, v208
	v_add_f32_e32 v209, 1.0, v209
	v_add_f32_e32 v210, 1.0, v210
	v_add_f32_e32 v211, 1.0, v211
	v_add_f32_e32 v212, 1.0, v212
	v_add_f32_e32 v213, 1.0, v213
	v_rcp_f32_e32 v110, v206
	v_rcp_f32_e32 v111, v207
	v_rcp_f32_e32 v112, v208
	v_rcp_f32_e32 v113, v209
	v_rcp_f32_e32 v117, v210
	v_rcp_f32_e32 v118, v211
	v_rcp_f32_e32 v119, v212
	v_rcp_f32_e32 v109, v213
	v_cvt_pk_bf16_f32 v106, v110, v111
	v_cvt_pk_bf16_f32 v107, v112, v113
	v_cvt_pk_bf16_f32 v108, v117, v118
	v_cvt_pk_bf16_f32 v109, v119, v109
	global_store_dwordx4 v[114:115], v[106:109], off
	s_nop 1
	v_fma_f32 v206, v102, v116, v40
	v_fma_f32 v207, v103, v116, v41
	v_fma_f32 v208, v104, v116, v42
	v_fma_f32 v209, v105, v116, v43
	v_fma_f32 v210, v98, v116, v32
	v_fma_f32 v211, v99, v116, v33
	v_fma_f32 v212, v100, v116, v34
	v_fma_f32 v213, v101, v116, v35
	v_mul_f32_e32 v206, 0xbfb8aa3b, v206
	v_mul_f32_e32 v207, 0xbfb8aa3b, v207
	v_mul_f32_e32 v208, 0xbfb8aa3b, v208
	v_mul_f32_e32 v209, 0xbfb8aa3b, v209
	v_mul_f32_e32 v210, 0xbfb8aa3b, v210
	v_mul_f32_e32 v211, 0xbfb8aa3b, v211
	v_mul_f32_e32 v212, 0xbfb8aa3b, v212
	v_mul_f32_e32 v213, 0xbfb8aa3b, v213
	v_exp_f32_e32 v206, v206
	v_exp_f32_e32 v207, v207
	v_exp_f32_e32 v208, v208
	v_exp_f32_e32 v209, v209
	v_exp_f32_e32 v210, v210
	v_exp_f32_e32 v211, v211
	v_exp_f32_e32 v212, v212
	v_exp_f32_e32 v213, v213
	v_add_f32_e32 v206, 1.0, v206
	v_add_f32_e32 v207, 1.0, v207
	v_add_f32_e32 v208, 1.0, v208
	v_add_f32_e32 v209, 1.0, v209
	v_add_f32_e32 v210, 1.0, v210
	v_add_f32_e32 v211, 1.0, v211
	v_add_f32_e32 v212, 1.0, v212
	v_add_f32_e32 v213, 1.0, v213
	v_rcp_f32_e32 v102, v206
	v_rcp_f32_e32 v103, v207
	v_rcp_f32_e32 v104, v208
	v_rcp_f32_e32 v105, v209
	v_rcp_f32_e32 v106, v210
	v_rcp_f32_e32 v107, v211
	v_rcp_f32_e32 v108, v212
	v_rcp_f32_e32 v101, v213
	v_cvt_pk_bf16_f32 v98, v102, v103
	v_cvt_pk_bf16_f32 v99, v104, v105
	v_cvt_pk_bf16_f32 v100, v106, v107
	v_cvt_pk_bf16_f32 v101, v108, v101
	global_store_dwordx4 v[114:115], v[98:101], off offset:256
	s_nop 1
	v_fmamk_f32 v98, v175, 0x3a800000, v223
	v_rsq_f32_e32 v100, v98
	v_mad_i64_i32 v[98:99], s[0:1], v174, s89, v[156:157]
	v_lshl_add_u64 v[98:99], v[98:99], 0, v[158:159]
	v_fma_f32 v206, v92, v100, v52
	v_fma_f32 v207, v93, v100, v53
	v_fma_f32 v208, v94, v100, v54
	v_fma_f32 v209, v95, v100, v55
	v_fma_f32 v210, v88, v100, v44
	v_fma_f32 v211, v89, v100, v45
	v_fma_f32 v212, v90, v100, v46
	v_fma_f32 v213, v91, v100, v47
	v_mul_f32_e32 v206, 0xbfb8aa3b, v206
	v_mul_f32_e32 v207, 0xbfb8aa3b, v207
	v_mul_f32_e32 v208, 0xbfb8aa3b, v208
	v_mul_f32_e32 v209, 0xbfb8aa3b, v209
	v_mul_f32_e32 v210, 0xbfb8aa3b, v210
	v_mul_f32_e32 v211, 0xbfb8aa3b, v211
	v_mul_f32_e32 v212, 0xbfb8aa3b, v212
	v_mul_f32_e32 v213, 0xbfb8aa3b, v213
	v_exp_f32_e32 v206, v206
	v_exp_f32_e32 v207, v207
	v_exp_f32_e32 v208, v208
	v_exp_f32_e32 v209, v209
	v_exp_f32_e32 v210, v210
	v_exp_f32_e32 v211, v211
	v_exp_f32_e32 v212, v212
	v_exp_f32_e32 v213, v213
	v_add_f32_e32 v206, 1.0, v206
	v_add_f32_e32 v207, 1.0, v207
	v_add_f32_e32 v208, 1.0, v208
	v_add_f32_e32 v209, 1.0, v209
	v_add_f32_e32 v210, 1.0, v210
	v_add_f32_e32 v211, 1.0, v211
; __device__ __forceinline__ u32x4 pack8(const float* f) { u32x4 w; w.x = cvt_pk_bf16(f[0], f[1]); w.y = cvt_pk_bf16(f[2], f[3]); w.z = cvt_pk_bf16(f[4], f[5]); w.w = cvt_pk_bf16(f[6], f[7]); return w; }
;     __device__ __forceinline__ void operator()(AccT& acc, const Unit& u, int wr, int wc, int fr, int fq) const {
;         const bool gate = u.pn >= 5;
;         const int col0 = u.pn * 256 + wc * 32 + 8 * fq;
;         f32x4 gb[2][2];
; #pragma unroll
;         for (int bj = 0; bj < 2; ++bj)
; #pragma unroll
;             for (int n = 0; n < 2; ++n) gb[bj][n] = gate ? *(const f32x4*)(gbias + (col0 - 1280) + bj * 128 + 4 * n) : (f32x4){0.f, 0.f, 0.f, 0.f};
;         float rsv[2][4];
; #pragma unroll
;         for (int ai = 0; ai < 2; ++ai)
; #pragma unroll
;             for (int m = 0; m < 4; ++m) rsv[ai][m] = ssq[u.pm * 256 + ai * 128 + wr * 64 + m * 16 + fr];
; #pragma unroll
;         for (int ai = 0; ai < 2; ++ai)
; #pragma unroll
;             for (int m = 0; m < 4; ++m) {
;                 const int row = u.pm * 256 + ai * 128 + wr * 64 + m * 16 + fr;
;                 const float rs = __builtin_amdgcn_rsqf(rsv[ai][m] * (1.0f / 1024.0f) + EPS);
;                 bf16_t* rowp = P + (size_t)row * INW + col0;
; #pragma unroll
;                 for (int bj = 0; bj < 2; ++bj) {
;                     float v[8];
; #pragma unroll
;                     for (int n = 0; n < 2; ++n)
; #pragma unroll
;                         for (int j = 0; j < 4; ++j) {
;                             float x = acc[ai][bj][m][n][j] * rs;
;                             if (gate) { x += gb[bj][n][j]; x = __builtin_amdgcn_rcpf(1.0f + __builtin_amdgcn_exp2f(-LOG2E * x)); }
;                             v[n * 4 + j] = x;
;                         }
;                     *(u32x4*)(rowp + bj * 128) = pack8(v);
;                 }
;             }
;     }
	v_add_f32_e32 v212, 1.0, v212
	v_add_f32_e32 v213, 1.0, v213
	v_rcp_f32_e32 v92, v206
	v_rcp_f32_e32 v93, v207
	v_rcp_f32_e32 v94, v208
	v_rcp_f32_e32 v95, v209
	v_rcp_f32_e32 v101, v210
	v_rcp_f32_e32 v102, v211
	v_rcp_f32_e32 v103, v212
	v_rcp_f32_e32 v91, v213
	v_cvt_pk_bf16_f32 v88, v92, v93
	v_cvt_pk_bf16_f32 v89, v94, v95
	v_cvt_pk_bf16_f32 v90, v101, v102
	v_cvt_pk_bf16_f32 v91, v103, v91
	global_store_dwordx4 v[98:99], v[88:91], off
	s_nop 1
	v_fma_f32 v206, v84, v100, v40
	v_fma_f32 v207, v85, v100, v41
	v_fma_f32 v208, v86, v100, v42
	v_fma_f32 v209, v87, v100, v43
	v_fma_f32 v210, v80, v100, v32
	v_fma_f32 v211, v81, v100, v33
	v_fma_f32 v212, v82, v100, v34
	v_fma_f32 v213, v83, v100, v35
	v_mul_f32_e32 v206, 0xbfb8aa3b, v206
	v_mul_f32_e32 v207, 0xbfb8aa3b, v207
	v_mul_f32_e32 v208, 0xbfb8aa3b, v208
	v_mul_f32_e32 v209, 0xbfb8aa3b, v209
	v_mul_f32_e32 v210, 0xbfb8aa3b, v210
	v_mul_f32_e32 v211, 0xbfb8aa3b, v211
	v_mul_f32_e32 v212, 0xbfb8aa3b, v212
	v_mul_f32_e32 v213, 0xbfb8aa3b, v213
	v_exp_f32_e32 v206, v206
	v_exp_f32_e32 v207, v207
	v_exp_f32_e32 v208, v208
	v_exp_f32_e32 v209, v209
	v_exp_f32_e32 v210, v210
	v_exp_f32_e32 v211, v211
	v_exp_f32_e32 v212, v212
	v_exp_f32_e32 v213, v213
	v_add_f32_e32 v206, 1.0, v206
	v_add_f32_e32 v207, 1.0, v207
	v_add_f32_e32 v208, 1.0, v208
	v_add_f32_e32 v209, 1.0, v209
	v_add_f32_e32 v210, 1.0, v210
	v_add_f32_e32 v211, 1.0, v211
	v_add_f32_e32 v212, 1.0, v212
	v_add_f32_e32 v213, 1.0, v213
	v_rcp_f32_e32 v84, v206
	v_rcp_f32_e32 v85, v207
	v_rcp_f32_e32 v86, v208
	v_rcp_f32_e32 v87, v209
	v_rcp_f32_e32 v88, v210
	v_rcp_f32_e32 v89, v211
	v_rcp_f32_e32 v90, v212
	v_rcp_f32_e32 v83, v213
	v_cvt_pk_bf16_f32 v80, v84, v85
	v_cvt_pk_bf16_f32 v81, v86, v87
	v_cvt_pk_bf16_f32 v82, v88, v89
	v_cvt_pk_bf16_f32 v83, v90, v83
	global_store_dwordx4 v[98:99], v[80:83], off offset:256
	s_nop 1
	v_fmamk_f32 v80, v173, 0x3a800000, v223
	v_rsq_f32_e32 v82, v80
	v_mad_i64_i32 v[80:81], s[0:1], v172, s89, v[156:157]
	v_lshl_add_u64 v[80:81], v[80:81], 0, v[158:159]
	v_fma_f32 v206, v76, v82, v52
	v_fma_f32 v207, v77, v82, v53
	v_fma_f32 v208, v78, v82, v54
	v_fma_f32 v209, v79, v82, v55
	v_fma_f32 v210, v72, v82, v44
	v_fma_f32 v211, v73, v82, v45
	v_fma_f32 v212, v74, v82, v46
	v_fma_f32 v213, v75, v82, v47
	v_mul_f32_e32 v206, 0xbfb8aa3b, v206
	v_mul_f32_e32 v207, 0xbfb8aa3b, v207
	v_mul_f32_e32 v208, 0xbfb8aa3b, v208
	v_mul_f32_e32 v209, 0xbfb8aa3b, v209
	v_mul_f32_e32 v210, 0xbfb8aa3b, v210
	v_mul_f32_e32 v211, 0xbfb8aa3b, v211
	v_mul_f32_e32 v212, 0xbfb8aa3b, v212
	v_mul_f32_e32 v213, 0xbfb8aa3b, v213
	v_exp_f32_e32 v206, v206
	v_exp_f32_e32 v207, v207
	v_exp_f32_e32 v208, v208
	v_exp_f32_e32 v209, v209
	v_exp_f32_e32 v210, v210
	v_exp_f32_e32 v211, v211
	v_exp_f32_e32 v212, v212
	v_exp_f32_e32 v213, v213
	v_add_f32_e32 v206, 1.0, v206
	v_add_f32_e32 v207, 1.0, v207
	v_add_f32_e32 v208, 1.0, v208
	v_add_f32_e32 v209, 1.0, v209
	v_add_f32_e32 v210, 1.0, v210
	v_add_f32_e32 v211, 1.0, v211
	v_add_f32_e32 v212, 1.0, v212
	v_add_f32_e32 v213, 1.0, v213
	v_rcp_f32_e32 v76, v206
	v_rcp_f32_e32 v77, v207
	v_rcp_f32_e32 v78, v208
	v_rcp_f32_e32 v79, v209
	v_rcp_f32_e32 v83, v210
	v_rcp_f32_e32 v84, v211
	v_rcp_f32_e32 v85, v212
	v_rcp_f32_e32 v75, v213
	v_cvt_pk_bf16_f32 v72, v76, v77
	v_cvt_pk_bf16_f32 v73, v78, v79
	v_cvt_pk_bf16_f32 v74, v83, v84
	v_cvt_pk_bf16_f32 v75, v85, v75
	global_store_dwordx4 v[80:81], v[72:75], off
	s_nop 1
	v_fma_f32 v206, v68, v82, v40
	v_fma_f32 v207, v69, v82, v41
	v_fma_f32 v208, v70, v82, v42
	v_fma_f32 v209, v71, v82, v43
	v_fma_f32 v210, v64, v82, v32
	v_fma_f32 v211, v65, v82, v33
	v_fma_f32 v212, v66, v82, v34
	v_fma_f32 v213, v67, v82, v35
	v_mul_f32_e32 v206, 0xbfb8aa3b, v206
	v_mul_f32_e32 v207, 0xbfb8aa3b, v207
	v_mul_f32_e32 v208, 0xbfb8aa3b, v208
	v_mul_f32_e32 v209, 0xbfb8aa3b, v209
	v_mul_f32_e32 v210, 0xbfb8aa3b, v210
	v_mul_f32_e32 v211, 0xbfb8aa3b, v211
	v_mul_f32_e32 v212, 0xbfb8aa3b, v212
	v_mul_f32_e32 v213, 0xbfb8aa3b, v213
	v_exp_f32_e32 v206, v206
	v_exp_f32_e32 v207, v207
	v_exp_f32_e32 v208, v208
	v_exp_f32_e32 v209, v209
	v_exp_f32_e32 v210, v210
	v_exp_f32_e32 v211, v211
	v_exp_f32_e32 v212, v212
	v_exp_f32_e32 v213, v213
	v_add_f32_e32 v206, 1.0, v206
	v_add_f32_e32 v207, 1.0, v207
	v_add_f32_e32 v208, 1.0, v208
	v_add_f32_e32 v209, 1.0, v209
	v_add_f32_e32 v210, 1.0, v210
	v_add_f32_e32 v211, 1.0, v211
	v_add_f32_e32 v212, 1.0, v212
	v_add_f32_e32 v213, 1.0, v213
	v_rcp_f32_e32 v68, v206
	v_rcp_f32_e32 v69, v207
	v_rcp_f32_e32 v70, v208
	v_rcp_f32_e32 v71, v209
	v_rcp_f32_e32 v72, v210
	v_rcp_f32_e32 v73, v211
	v_rcp_f32_e32 v74, v212
	v_rcp_f32_e32 v67, v213
	v_cvt_pk_bf16_f32 v64, v68, v69
	v_cvt_pk_bf16_f32 v65, v70, v71
	v_cvt_pk_bf16_f32 v66, v72, v73
	v_cvt_pk_bf16_f32 v67, v74, v67
	global_store_dwordx4 v[80:81], v[64:67], off offset:256
	s_nop 1
	v_fmamk_f32 v64, v171, 0x3a800000, v223
	v_rsq_f32_e32 v66, v64
	v_mad_i64_i32 v[64:65], s[0:1], v170, s89, v[156:157]
	v_lshl_add_u64 v[64:65], v[64:65], 0, v[158:159]
	v_fma_f32 v206, v60, v66, v52
	v_fma_f32 v207, v61, v66, v53
	v_fma_f32 v208, v62, v66, v54
	v_fma_f32 v209, v63, v66, v55
	v_fma_f32 v210, v56, v66, v44
	v_fma_f32 v211, v57, v66, v45
	v_fma_f32 v212, v58, v66, v46
	v_fma_f32 v213, v59, v66, v47
	v_mul_f32_e32 v206, 0xbfb8aa3b, v206
	v_mul_f32_e32 v207, 0xbfb8aa3b, v207
	v_mul_f32_e32 v208, 0xbfb8aa3b, v208
	v_mul_f32_e32 v209, 0xbfb8aa3b, v209
	v_mul_f32_e32 v210, 0xbfb8aa3b, v210
	v_mul_f32_e32 v211, 0xbfb8aa3b, v211
	v_mul_f32_e32 v212, 0xbfb8aa3b, v212
	v_mul_f32_e32 v213, 0xbfb8aa3b, v213
	v_exp_f32_e32 v206, v206
	v_exp_f32_e32 v207, v207
	v_exp_f32_e32 v208, v208
; __device__ __forceinline__ u32x4 pack8(const float* f) { u32x4 w; w.x = cvt_pk_bf16(f[0], f[1]); w.y = cvt_pk_bf16(f[2], f[3]); w.z = cvt_pk_bf16(f[4], f[5]); w.w = cvt_pk_bf16(f[6], f[7]); return w; }
;     __device__ __forceinline__ void operator()(AccT& acc, const Unit& u, int wr, int wc, int fr, int fq) const {
;         const bool gate = u.pn >= 5;
;         const int col0 = u.pn * 256 + wc * 32 + 8 * fq;
;         f32x4 gb[2][2];
; #pragma unroll
;         for (int bj = 0; bj < 2; ++bj)
; #pragma unroll
;             for (int n = 0; n < 2; ++n) gb[bj][n] = gate ? *(const f32x4*)(gbias + (col0 - 1280) + bj * 128 + 4 * n) : (f32x4){0.f, 0.f, 0.f, 0.f};
;         float rsv[2][4];
; #pragma unroll
;         for (int ai = 0; ai < 2; ++ai)
; #pragma unroll
;             for (int m = 0; m < 4; ++m) rsv[ai][m] = ssq[u.pm * 256 + ai * 128 + wr * 64 + m * 16 + fr];
; #pragma unroll
;         for (int ai = 0; ai < 2; ++ai)
; #pragma unroll
;             for (int m = 0; m < 4; ++m) {
;                 const int row = u.pm * 256 + ai * 128 + wr * 64 + m * 16 + fr;
;                 const float rs = __builtin_amdgcn_rsqf(rsv[ai][m] * (1.0f / 1024.0f) + EPS);
;                 bf16_t* rowp = P + (size_t)row * INW + col0;
; #pragma unroll
;                 for (int bj = 0; bj < 2; ++bj) {
;                     float v[8];
; #pragma unroll
;                     for (int n = 0; n < 2; ++n)
; #pragma unroll
;                         for (int j = 0; j < 4; ++j) {
;                             float x = acc[ai][bj][m][n][j] * rs;
;                             if (gate) { x += gb[bj][n][j]; x = __builtin_amdgcn_rcpf(1.0f + __builtin_amdgcn_exp2f(-LOG2E * x)); }
;                             v[n * 4 + j] = x;
;                         }
;                     *(u32x4*)(rowp + bj * 128) = pack8(v);
;                 }
;             }
;     }
	v_exp_f32_e32 v209, v209
	v_exp_f32_e32 v210, v210
	v_exp_f32_e32 v211, v211
	v_exp_f32_e32 v212, v212
	v_exp_f32_e32 v213, v213
	v_add_f32_e32 v206, 1.0, v206
	v_add_f32_e32 v207, 1.0, v207
	v_add_f32_e32 v208, 1.0, v208
	v_add_f32_e32 v209, 1.0, v209
	v_add_f32_e32 v210, 1.0, v210
	v_add_f32_e32 v211, 1.0, v211
	v_add_f32_e32 v212, 1.0, v212
	v_add_f32_e32 v213, 1.0, v213
	v_rcp_f32_e32 v60, v206
	v_rcp_f32_e32 v61, v207
	v_rcp_f32_e32 v62, v208
	v_rcp_f32_e32 v63, v209
	v_rcp_f32_e32 v67, v210
	v_rcp_f32_e32 v68, v211
	v_rcp_f32_e32 v69, v212
	v_rcp_f32_e32 v59, v213
	v_cvt_pk_bf16_f32 v56, v60, v61
	v_cvt_pk_bf16_f32 v57, v62, v63
	v_cvt_pk_bf16_f32 v58, v67, v68
	v_cvt_pk_bf16_f32 v59, v69, v59
	global_store_dwordx4 v[64:65], v[56:59], off
	s_nop 1
	v_fma_f32 v206, v48, v66, v40
	v_fma_f32 v207, v49, v66, v41
	v_fma_f32 v208, v50, v66, v42
	v_fma_f32 v209, v51, v66, v43
	v_fma_f32 v210, v36, v66, v32
	v_fma_f32 v211, v37, v66, v33
	v_fma_f32 v212, v38, v66, v34
	v_fma_f32 v213, v39, v66, v35
	v_mul_f32_e32 v206, 0xbfb8aa3b, v206
	v_mul_f32_e32 v207, 0xbfb8aa3b, v207
	v_mul_f32_e32 v208, 0xbfb8aa3b, v208
	v_mul_f32_e32 v209, 0xbfb8aa3b, v209
	v_mul_f32_e32 v210, 0xbfb8aa3b, v210
	v_mul_f32_e32 v211, 0xbfb8aa3b, v211
	v_mul_f32_e32 v212, 0xbfb8aa3b, v212
	v_mul_f32_e32 v213, 0xbfb8aa3b, v213
	v_exp_f32_e32 v206, v206
	v_exp_f32_e32 v207, v207
	v_exp_f32_e32 v208, v208
	v_exp_f32_e32 v209, v209
	v_exp_f32_e32 v210, v210
	v_exp_f32_e32 v211, v211
	v_exp_f32_e32 v212, v212
	v_exp_f32_e32 v213, v213
	v_add_f32_e32 v206, 1.0, v206
	v_add_f32_e32 v207, 1.0, v207
	v_add_f32_e32 v208, 1.0, v208
	v_add_f32_e32 v209, 1.0, v209
	v_add_f32_e32 v210, 1.0, v210
	v_add_f32_e32 v211, 1.0, v211
	v_add_f32_e32 v212, 1.0, v212
	v_add_f32_e32 v213, 1.0, v213
	v_rcp_f32_e32 v48, v206
	v_rcp_f32_e32 v49, v207
	v_rcp_f32_e32 v50, v208
	v_rcp_f32_e32 v51, v209
	v_rcp_f32_e32 v56, v210
	v_rcp_f32_e32 v57, v211
	v_rcp_f32_e32 v58, v212
	v_rcp_f32_e32 v39, v213
	v_cvt_pk_bf16_f32 v36, v48, v49
	v_cvt_pk_bf16_f32 v37, v50, v51
	v_cvt_pk_bf16_f32 v38, v56, v57
	v_cvt_pk_bf16_f32 v39, v58, v39
	global_store_dwordx4 v[64:65], v[36:39], off offset:256
	s_nop 1
	v_fmamk_f32 v36, v169, 0x3a800000, v223
	v_rsq_f32_e32 v38, v36
	v_mad_i64_i32 v[36:37], s[0:1], v168, s89, v[156:157]
	v_lshl_add_u64 v[36:37], v[36:37], 0, v[158:159]
	v_fma_f32 v206, v28, v38, v52
	v_fma_f32 v207, v29, v38, v53
	v_fma_f32 v208, v30, v38, v54
	v_fma_f32 v209, v31, v38, v55
	v_fma_f32 v210, v24, v38, v44
	v_fma_f32 v211, v25, v38, v45
	v_fma_f32 v212, v26, v38, v46
	v_fma_f32 v213, v27, v38, v47
	v_mul_f32_e32 v206, 0xbfb8aa3b, v206
	v_mul_f32_e32 v207, 0xbfb8aa3b, v207
	v_mul_f32_e32 v208, 0xbfb8aa3b, v208
	v_mul_f32_e32 v209, 0xbfb8aa3b, v209
	v_mul_f32_e32 v210, 0xbfb8aa3b, v210
	v_mul_f32_e32 v211, 0xbfb8aa3b, v211
	v_mul_f32_e32 v212, 0xbfb8aa3b, v212
	v_mul_f32_e32 v213, 0xbfb8aa3b, v213
	v_exp_f32_e32 v206, v206
	v_exp_f32_e32 v207, v207
	v_exp_f32_e32 v208, v208
	v_exp_f32_e32 v209, v209
	v_exp_f32_e32 v210, v210
	v_exp_f32_e32 v211, v211
	v_exp_f32_e32 v212, v212
	v_exp_f32_e32 v213, v213
	v_add_f32_e32 v206, 1.0, v206
	v_add_f32_e32 v207, 1.0, v207
	v_add_f32_e32 v208, 1.0, v208
	v_add_f32_e32 v209, 1.0, v209
	v_add_f32_e32 v210, 1.0, v210
	v_add_f32_e32 v211, 1.0, v211
	v_add_f32_e32 v212, 1.0, v212
	v_add_f32_e32 v213, 1.0, v213
	v_rcp_f32_e32 v28, v206
	v_rcp_f32_e32 v29, v207
	v_rcp_f32_e32 v30, v208
	v_rcp_f32_e32 v31, v209
	v_rcp_f32_e32 v39, v210
	v_rcp_f32_e32 v48, v211
	v_rcp_f32_e32 v49, v212
	v_rcp_f32_e32 v27, v213
	v_cvt_pk_bf16_f32 v24, v28, v29
	v_cvt_pk_bf16_f32 v25, v30, v31
	v_cvt_pk_bf16_f32 v26, v39, v48
	v_cvt_pk_bf16_f32 v27, v49, v27
	global_store_dwordx4 v[36:37], v[24:27], off
	s_nop 1
	v_fma_f32 v206, v20, v38, v40
	v_fma_f32 v207, v21, v38, v41
	v_fma_f32 v208, v22, v38, v42
	v_fma_f32 v209, v23, v38, v43
	v_fma_f32 v210, v16, v38, v32
	v_fma_f32 v211, v17, v38, v33
	v_fma_f32 v212, v18, v38, v34
	v_fma_f32 v213, v19, v38, v35
	v_mul_f32_e32 v206, 0xbfb8aa3b, v206
	v_mul_f32_e32 v207, 0xbfb8aa3b, v207
	v_mul_f32_e32 v208, 0xbfb8aa3b, v208
	v_mul_f32_e32 v209, 0xbfb8aa3b, v209
	v_mul_f32_e32 v210, 0xbfb8aa3b, v210
	v_mul_f32_e32 v211, 0xbfb8aa3b, v211
	v_mul_f32_e32 v212, 0xbfb8aa3b, v212
	v_mul_f32_e32 v213, 0xbfb8aa3b, v213
	v_exp_f32_e32 v206, v206
	v_exp_f32_e32 v207, v207
	v_exp_f32_e32 v208, v208
	v_exp_f32_e32 v209, v209
	v_exp_f32_e32 v210, v210
	v_exp_f32_e32 v211, v211
	v_exp_f32_e32 v212, v212
	v_exp_f32_e32 v213, v213
	v_add_f32_e32 v206, 1.0, v206
	v_add_f32_e32 v207, 1.0, v207
	v_add_f32_e32 v208, 1.0, v208
	v_add_f32_e32 v209, 1.0, v209
	v_add_f32_e32 v210, 1.0, v210
	v_add_f32_e32 v211, 1.0, v211
	v_add_f32_e32 v212, 1.0, v212
	v_add_f32_e32 v213, 1.0, v213
	v_rcp_f32_e32 v20, v206
	v_rcp_f32_e32 v21, v207
	v_rcp_f32_e32 v22, v208
	v_rcp_f32_e32 v23, v209
	v_rcp_f32_e32 v24, v210
	v_rcp_f32_e32 v25, v211
	v_rcp_f32_e32 v26, v212
	v_rcp_f32_e32 v19, v213
	v_cvt_pk_bf16_f32 v16, v20, v21
	v_cvt_pk_bf16_f32 v17, v22, v23
	v_cvt_pk_bf16_f32 v18, v24, v25
	v_cvt_pk_bf16_f32 v19, v26, v19
	global_store_dwordx4 v[36:37], v[16:19], off offset:256
	s_nop 1
	v_fmamk_f32 v16, v167, 0x3a800000, v223
	v_rsq_f32_e32 v18, v16
	v_mad_i64_i32 v[16:17], s[0:1], v166, s89, v[156:157]
	v_lshl_add_u64 v[16:17], v[16:17], 0, v[158:159]
	v_fmac_f32_e32 v52, v12, v18
	v_mul_f32_e32 v19, v12, v18
	v_mul_f32_e32 v12, 0xbfb8aa3b, v52
	v_exp_f32_e32 v12, v12
	v_fmac_f32_e32 v53, v13, v18
	v_fmac_f32_e32 v54, v14, v18
	v_fmac_f32_e32 v55, v15, v18
	v_add_f32_e32 v12, 1.0, v12
	v_rcp_f32_e32 v12, v12
	v_fmac_f32_e32 v44, v8, v18
	v_fmac_f32_e32 v45, v9, v18
; __device__ __forceinline__ u32x4 pack8(const float* f) { u32x4 w; w.x = cvt_pk_bf16(f[0], f[1]); w.y = cvt_pk_bf16(f[2], f[3]); w.z = cvt_pk_bf16(f[4], f[5]); w.w = cvt_pk_bf16(f[6], f[7]); return w; }
;     __device__ __forceinline__ void operator()(AccT& acc, const Unit& u, int wr, int wc, int fr, int fq) const {
;         const bool gate = u.pn >= 5;
;         const int col0 = u.pn * 256 + wc * 32 + 8 * fq;
;         f32x4 gb[2][2];
; #pragma unroll
;         for (int bj = 0; bj < 2; ++bj)
; #pragma unroll
;             for (int n = 0; n < 2; ++n) gb[bj][n] = gate ? *(const f32x4*)(gbias + (col0 - 1280) + bj * 128 + 4 * n) : (f32x4){0.f, 0.f, 0.f, 0.f};
;         float rsv[2][4];
; #pragma unroll
;         for (int ai = 0; ai < 2; ++ai)
; #pragma unroll
;             for (int m = 0; m < 4; ++m) rsv[ai][m] = ssq[u.pm * 256 + ai * 128 + wr * 64 + m * 16 + fr];
; #pragma unroll
;         for (int ai = 0; ai < 2; ++ai)
; #pragma unroll
;             for (int m = 0; m < 4; ++m) {
;                 const int row = u.pm * 256 + ai * 128 + wr * 64 + m * 16 + fr;
;                 const float rs = __builtin_amdgcn_rsqf(rsv[ai][m] * (1.0f / 1024.0f) + EPS);
;                 bf16_t* rowp = P + (size_t)row * INW + col0;
; #pragma unroll
;                 for (int bj = 0; bj < 2; ++bj) {
;                     float v[8];
; #pragma unroll
;                     for (int n = 0; n < 2; ++n)
; #pragma unroll
;                         for (int j = 0; j < 4; ++j) {
;                             float x = acc[ai][bj][m][n][j] * rs;
;                             if (gate) { x += gb[bj][n][j]; x = __builtin_amdgcn_rcpf(1.0f + __builtin_amdgcn_exp2f(-LOG2E * x)); }
;                             v[n * 4 + j] = x;
;                         }
;                     *(u32x4*)(rowp + bj * 128) = pack8(v);
;                 }
;             }
;     }
	v_fmac_f32_e32 v46, v10, v18
	v_cndmask_b32_e64 v12, v19, v12, s[42:43]
	v_mul_f32_e32 v19, v13, v18
	v_mul_f32_e32 v13, 0xbfb8aa3b, v53
	v_exp_f32_e32 v13, v13
	v_fmac_f32_e32 v47, v11, v18
	v_fmac_f32_e32 v40, v4, v18
	v_fmac_f32_e32 v41, v5, v18
	v_add_f32_e32 v13, 1.0, v13
	v_rcp_f32_e32 v13, v13
	v_fmac_f32_e32 v42, v6, v18
	v_fmac_f32_e32 v43, v7, v18
	v_fmac_f32_e32 v32, v0, v18
	v_cndmask_b32_e64 v13, v19, v13, s[42:43]
	v_mul_f32_e32 v19, v14, v18
	v_mul_f32_e32 v14, 0xbfb8aa3b, v54
	v_exp_f32_e32 v14, v14
	v_fmac_f32_e32 v33, v1, v18
	v_fmac_f32_e32 v34, v2, v18
	v_fmac_f32_e32 v35, v3, v18
	v_add_f32_e32 v14, 1.0, v14
	v_rcp_f32_e32 v14, v14
	s_mov_b64 s[0:1], -1
	v_cndmask_b32_e64 v14, v19, v14, s[42:43]
	v_mul_f32_e32 v19, v15, v18
	v_mul_f32_e32 v15, 0xbfb8aa3b, v55
	v_exp_f32_e32 v15, v15
	s_nop 0
	v_add_f32_e32 v15, 1.0, v15
	v_rcp_f32_e32 v15, v15
	s_nop 0
	v_cndmask_b32_e64 v15, v19, v15, s[42:43]
	v_mul_f32_e32 v19, v8, v18
	v_mul_f32_e32 v8, 0xbfb8aa3b, v44
	v_exp_f32_e32 v8, v8
	s_nop 0
	v_add_f32_e32 v8, 1.0, v8
	v_rcp_f32_e32 v8, v8
	s_nop 0
	v_cndmask_b32_e64 v19, v19, v8, s[42:43]
	v_mul_f32_e32 v8, v9, v18
	v_mul_f32_e32 v9, 0xbfb8aa3b, v45
	v_exp_f32_e32 v9, v9
	s_nop 0
	v_add_f32_e32 v9, 1.0, v9
	v_rcp_f32_e32 v9, v9
	s_nop 0
	v_cndmask_b32_e64 v20, v8, v9, s[42:43]
	v_mul_f32_e32 v9, 0xbfb8aa3b, v46
	v_exp_f32_e32 v9, v9
	v_mul_f32_e32 v8, v10, v18
	v_add_f32_e32 v9, 1.0, v9
	v_rcp_f32_e32 v9, v9
	s_nop 0
	v_cndmask_b32_e64 v21, v8, v9, s[42:43]
	v_mul_f32_e32 v9, 0xbfb8aa3b, v47
	v_exp_f32_e32 v9, v9
	v_mul_f32_e32 v8, v11, v18
	v_add_f32_e32 v9, 1.0, v9
	v_rcp_f32_e32 v9, v9
	s_nop 0
	v_cndmask_b32_e64 v11, v8, v9, s[42:43]
	v_cvt_pk_bf16_f32 v8, v12, v13
	v_cvt_pk_bf16_f32 v9, v14, v15
	v_cvt_pk_bf16_f32 v10, v19, v20
	v_cvt_pk_bf16_f32 v11, v21, v11
	global_store_dwordx4 v[16:17], v[8:11], off
	s_nop 1
	v_mul_f32_e32 v8, v4, v18
	v_mul_f32_e32 v4, 0xbfb8aa3b, v40
	v_exp_f32_e32 v4, v4
	s_nop 0
	v_add_f32_e32 v4, 1.0, v4
	v_rcp_f32_e32 v4, v4
	s_nop 0
	v_cndmask_b32_e64 v4, v8, v4, s[42:43]
	v_mul_f32_e32 v8, v5, v18
	v_mul_f32_e32 v5, 0xbfb8aa3b, v41
	v_exp_f32_e32 v5, v5
	s_nop 0
	v_add_f32_e32 v5, 1.0, v5
	v_rcp_f32_e32 v5, v5
	s_nop 0
	v_cndmask_b32_e64 v5, v8, v5, s[42:43]
	v_mul_f32_e32 v8, v6, v18
	v_mul_f32_e32 v6, 0xbfb8aa3b, v42
	v_exp_f32_e32 v6, v6
	s_nop 0
	v_add_f32_e32 v6, 1.0, v6
	v_rcp_f32_e32 v6, v6
	s_nop 0
	v_cndmask_b32_e64 v6, v8, v6, s[42:43]
	v_mul_f32_e32 v8, v7, v18
	v_mul_f32_e32 v7, 0xbfb8aa3b, v43
	v_exp_f32_e32 v7, v7
	s_nop 0
	v_add_f32_e32 v7, 1.0, v7
	v_rcp_f32_e32 v7, v7
	s_nop 0
	v_cndmask_b32_e64 v7, v8, v7, s[42:43]
	v_mul_f32_e32 v8, v0, v18
	v_mul_f32_e32 v0, 0xbfb8aa3b, v32
	v_exp_f32_e32 v0, v0
	s_nop 0
	v_add_f32_e32 v0, 1.0, v0
	v_rcp_f32_e32 v0, v0
	s_nop 0
	v_cndmask_b32_e64 v8, v8, v0, s[42:43]
	v_mul_f32_e32 v0, v1, v18
	v_mul_f32_e32 v1, 0xbfb8aa3b, v33
	v_exp_f32_e32 v1, v1
	s_nop 0
	v_add_f32_e32 v1, 1.0, v1
	v_rcp_f32_e32 v1, v1
	s_nop 0
	v_cndmask_b32_e64 v9, v0, v1, s[42:43]
	v_mul_f32_e32 v1, 0xbfb8aa3b, v34
	v_exp_f32_e32 v1, v1
	v_mul_f32_e32 v0, v2, v18
	v_add_f32_e32 v1, 1.0, v1
	v_rcp_f32_e32 v1, v1
	s_nop 0
	v_cndmask_b32_e64 v10, v0, v1, s[42:43]
	v_mul_f32_e32 v1, 0xbfb8aa3b, v35
	v_exp_f32_e32 v1, v1
	v_mul_f32_e32 v0, v3, v18
	v_add_f32_e32 v1, 1.0, v1
	v_rcp_f32_e32 v1, v1
	s_nop 0
	v_cndmask_b32_e64 v3, v0, v1, s[42:43]
	v_cvt_pk_bf16_f32 v0, v4, v5
	v_cvt_pk_bf16_f32 v1, v6, v7
	v_cvt_pk_bf16_f32 v2, v8, v9
	v_cvt_pk_bf16_f32 v3, v10, v3
	global_store_dwordx4 v[16:17], v[0:3], off offset:256
	s_branch .Lmy_p1_join
.Lmy_p1_nongate:
	v_fmamk_f32 v156, v161, 0x3a800000, v223
	v_rsq_f32_e32 v180, v156
	v_mov_b64_e32 v[156:157], s[84:85]
	v_mad_i64_i32 v[160:161], s[0:1], v160, s89, v[156:157]
	v_lshl_add_u64 v[160:161], v[160:161], 0, v[158:159]
	v_mul_f32_e32 v142, v142, v180
	v_mul_f32_e32 v143, v143, v180
	v_mul_f32_e32 v144, v144, v180
	v_mul_f32_e32 v145, v145, v180
	v_mul_f32_e32 v181, v138, v180
	v_mul_f32_e32 v182, v139, v180
	v_mul_f32_e32 v183, v140, v180
	v_mul_f32_e32 v141, v141, v180
	v_cvt_pk_bf16_f32 v138, v142, v143
	v_cvt_pk_bf16_f32 v139, v144, v145
	v_cvt_pk_bf16_f32 v140, v181, v182
	v_cvt_pk_bf16_f32 v141, v183, v141
	global_store_dwordx4 v[160:161], v[138:141], off
	s_nop 1
	v_mul_f32_e32 v134, v134, v180
	v_mul_f32_e32 v135, v135, v180
	v_mul_f32_e32 v136, v136, v180
	v_mul_f32_e32 v137, v137, v180
	v_mul_f32_e32 v138, v130, v180
	v_mul_f32_e32 v139, v131, v180
	v_mul_f32_e32 v140, v132, v180
	v_mul_f32_e32 v133, v133, v180
	v_cvt_pk_bf16_f32 v130, v134, v135
	v_cvt_pk_bf16_f32 v131, v136, v137
	v_cvt_pk_bf16_f32 v132, v138, v139
	v_cvt_pk_bf16_f32 v133, v140, v133
	global_store_dwordx4 v[160:161], v[130:133], off offset:256
	s_nop 1
	v_fmamk_f32 v130, v179, 0x3a800000, v223
	v_rsq_f32_e32 v132, v130
	v_mad_i64_i32 v[130:131], s[0:1], v178, s89, v[156:157]
	v_lshl_add_u64 v[130:131], v[130:131], 0, v[158:159]
	v_mul_f32_e32 v126, v126, v132
	v_mul_f32_e32 v127, v127, v132
	v_mul_f32_e32 v128, v128, v132
	v_mul_f32_e32 v129, v129, v132
	v_mul_f32_e32 v133, v122, v132
	v_mul_f32_e32 v134, v123, v132
	v_mul_f32_e32 v135, v124, v132
	v_mul_f32_e32 v125, v125, v132
	v_cvt_pk_bf16_f32 v122, v126, v127
	v_cvt_pk_bf16_f32 v123, v128, v129
	v_cvt_pk_bf16_f32 v124, v133, v134
	v_cvt_pk_bf16_f32 v125, v135, v125
	global_store_dwordx4 v[130:131], v[122:125], off
	s_nop 1
	v_mul_f32_e32 v118, v118, v132
	v_mul_f32_e32 v119, v119, v132
	v_mul_f32_e32 v120, v120, v132
	v_mul_f32_e32 v121, v121, v132
	v_mul_f32_e32 v122, v114, v132
	v_mul_f32_e32 v123, v115, v132
	v_mul_f32_e32 v124, v116, v132
	v_mul_f32_e32 v117, v117, v132
; __device__ __forceinline__ u32x4 pack8(const float* f) { u32x4 w; w.x = cvt_pk_bf16(f[0], f[1]); w.y = cvt_pk_bf16(f[2], f[3]); w.z = cvt_pk_bf16(f[4], f[5]); w.w = cvt_pk_bf16(f[6], f[7]); return w; }
;     __device__ __forceinline__ void operator()(AccT& acc, const Unit& u, int wr, int wc, int fr, int fq) const {
;         const bool gate = u.pn >= 5;
;         const int col0 = u.pn * 256 + wc * 32 + 8 * fq;
;         f32x4 gb[2][2];
; #pragma unroll
;         for (int bj = 0; bj < 2; ++bj)
; #pragma unroll
;             for (int n = 0; n < 2; ++n) gb[bj][n] = gate ? *(const f32x4*)(gbias + (col0 - 1280) + bj * 128 + 4 * n) : (f32x4){0.f, 0.f, 0.f, 0.f};
;         float rsv[2][4];
; #pragma unroll
;         for (int ai = 0; ai < 2; ++ai)
; #pragma unroll
;             for (int m = 0; m < 4; ++m) rsv[ai][m] = ssq[u.pm * 256 + ai * 128 + wr * 64 + m * 16 + fr];
; #pragma unroll
;         for (int ai = 0; ai < 2; ++ai)
; #pragma unroll
;             for (int m = 0; m < 4; ++m) {
;                 const int row = u.pm * 256 + ai * 128 + wr * 64 + m * 16 + fr;
;                 const float rs = __builtin_amdgcn_rsqf(rsv[ai][m] * (1.0f / 1024.0f) + EPS);
;                 bf16_t* rowp = P + (size_t)row * INW + col0;
; #pragma unroll
;                 for (int bj = 0; bj < 2; ++bj) {
;                     float v[8];
; #pragma unroll
;                     for (int n = 0; n < 2; ++n)
; #pragma unroll
;                         for (int j = 0; j < 4; ++j) {
;                             float x = acc[ai][bj][m][n][j] * rs;
;                             if (gate) { x += gb[bj][n][j]; x = __builtin_amdgcn_rcpf(1.0f + __builtin_amdgcn_exp2f(-LOG2E * x)); }
;                             v[n * 4 + j] = x;
;                         }
;                     *(u32x4*)(rowp + bj * 128) = pack8(v);
;                 }
;             }
;     }
	v_cvt_pk_bf16_f32 v114, v118, v119
	v_cvt_pk_bf16_f32 v115, v120, v121
	v_cvt_pk_bf16_f32 v116, v122, v123
	v_cvt_pk_bf16_f32 v117, v124, v117
	global_store_dwordx4 v[130:131], v[114:117], off offset:256
	s_nop 1
	v_fmamk_f32 v114, v177, 0x3a800000, v223
	v_rsq_f32_e32 v116, v114
	v_mad_i64_i32 v[114:115], s[0:1], v176, s89, v[156:157]
	v_lshl_add_u64 v[114:115], v[114:115], 0, v[158:159]
	v_mul_f32_e32 v110, v110, v116
	v_mul_f32_e32 v111, v111, v116
	v_mul_f32_e32 v112, v112, v116
	v_mul_f32_e32 v113, v113, v116
	v_mul_f32_e32 v117, v106, v116
	v_mul_f32_e32 v118, v107, v116
	v_mul_f32_e32 v119, v108, v116
	v_mul_f32_e32 v109, v109, v116
	v_cvt_pk_bf16_f32 v106, v110, v111
	v_cvt_pk_bf16_f32 v107, v112, v113
	v_cvt_pk_bf16_f32 v108, v117, v118
	v_cvt_pk_bf16_f32 v109, v119, v109
	global_store_dwordx4 v[114:115], v[106:109], off
	s_nop 1
	v_mul_f32_e32 v102, v102, v116
	v_mul_f32_e32 v103, v103, v116
	v_mul_f32_e32 v104, v104, v116
	v_mul_f32_e32 v105, v105, v116
	v_mul_f32_e32 v106, v98, v116
	v_mul_f32_e32 v107, v99, v116
	v_mul_f32_e32 v108, v100, v116
	v_mul_f32_e32 v101, v101, v116
	v_cvt_pk_bf16_f32 v98, v102, v103
	v_cvt_pk_bf16_f32 v99, v104, v105
	v_cvt_pk_bf16_f32 v100, v106, v107
	v_cvt_pk_bf16_f32 v101, v108, v101
	global_store_dwordx4 v[114:115], v[98:101], off offset:256
	s_nop 1
	v_fmamk_f32 v98, v175, 0x3a800000, v223
	v_rsq_f32_e32 v100, v98
	v_mad_i64_i32 v[98:99], s[0:1], v174, s89, v[156:157]
	v_lshl_add_u64 v[98:99], v[98:99], 0, v[158:159]
	v_mul_f32_e32 v92, v92, v100
	v_mul_f32_e32 v93, v93, v100
	v_mul_f32_e32 v94, v94, v100
	v_mul_f32_e32 v95, v95, v100
	v_mul_f32_e32 v101, v88, v100
	v_mul_f32_e32 v102, v89, v100
	v_mul_f32_e32 v103, v90, v100
	v_mul_f32_e32 v91, v91, v100
	v_cvt_pk_bf16_f32 v88, v92, v93
	v_cvt_pk_bf16_f32 v89, v94, v95
	v_cvt_pk_bf16_f32 v90, v101, v102
	v_cvt_pk_bf16_f32 v91, v103, v91
	global_store_dwordx4 v[98:99], v[88:91], off
	s_nop 1
	v_mul_f32_e32 v84, v84, v100
	v_mul_f32_e32 v85, v85, v100
	v_mul_f32_e32 v86, v86, v100
	v_mul_f32_e32 v87, v87, v100
	v_mul_f32_e32 v88, v80, v100
	v_mul_f32_e32 v89, v81, v100
	v_mul_f32_e32 v90, v82, v100
	v_mul_f32_e32 v83, v83, v100
	v_cvt_pk_bf16_f32 v80, v84, v85
	v_cvt_pk_bf16_f32 v81, v86, v87
	v_cvt_pk_bf16_f32 v82, v88, v89
	v_cvt_pk_bf16_f32 v83, v90, v83
	global_store_dwordx4 v[98:99], v[80:83], off offset:256
	s_nop 1
	v_fmamk_f32 v80, v173, 0x3a800000, v223
	v_rsq_f32_e32 v82, v80
	v_mad_i64_i32 v[80:81], s[0:1], v172, s89, v[156:157]
	v_lshl_add_u64 v[80:81], v[80:81], 0, v[158:159]
	v_mul_f32_e32 v76, v76, v82
	v_mul_f32_e32 v77, v77, v82
	v_mul_f32_e32 v78, v78, v82
	v_mul_f32_e32 v79, v79, v82
	v_mul_f32_e32 v83, v72, v82
	v_mul_f32_e32 v84, v73, v82
	v_mul_f32_e32 v85, v74, v82
	v_mul_f32_e32 v75, v75, v82
	v_cvt_pk_bf16_f32 v72, v76, v77
	v_cvt_pk_bf16_f32 v73, v78, v79
	v_cvt_pk_bf16_f32 v74, v83, v84
	v_cvt_pk_bf16_f32 v75, v85, v75
	global_store_dwordx4 v[80:81], v[72:75], off
	s_nop 1
	v_mul_f32_e32 v68, v68, v82
	v_mul_f32_e32 v69, v69, v82
	v_mul_f32_e32 v70, v70, v82
	v_mul_f32_e32 v71, v71, v82
	v_mul_f32_e32 v72, v64, v82
	v_mul_f32_e32 v73, v65, v82
	v_mul_f32_e32 v74, v66, v82
	v_mul_f32_e32 v67, v67, v82
	v_cvt_pk_bf16_f32 v64, v68, v69
	v_cvt_pk_bf16_f32 v65, v70, v71
	v_cvt_pk_bf16_f32 v66, v72, v73
	v_cvt_pk_bf16_f32 v67, v74, v67
	global_store_dwordx4 v[80:81], v[64:67], off offset:256
	s_nop 1
	v_fmamk_f32 v64, v171, 0x3a800000, v223
	v_rsq_f32_e32 v66, v64
	v_mad_i64_i32 v[64:65], s[0:1], v170, s89, v[156:157]
	v_lshl_add_u64 v[64:65], v[64:65], 0, v[158:159]
	v_mul_f32_e32 v60, v60, v66
	v_mul_f32_e32 v61, v61, v66
	v_mul_f32_e32 v62, v62, v66
	v_mul_f32_e32 v63, v63, v66
	v_mul_f32_e32 v67, v56, v66
	v_mul_f32_e32 v68, v57, v66
	v_mul_f32_e32 v69, v58, v66
	v_mul_f32_e32 v59, v59, v66
	v_cvt_pk_bf16_f32 v56, v60, v61
	v_cvt_pk_bf16_f32 v57, v62, v63
	v_cvt_pk_bf16_f32 v58, v67, v68
	v_cvt_pk_bf16_f32 v59, v69, v59
	global_store_dwordx4 v[64:65], v[56:59], off
	s_nop 1
	v_mul_f32_e32 v48, v48, v66
	v_mul_f32_e32 v49, v49, v66
	v_mul_f32_e32 v50, v50, v66
	v_mul_f32_e32 v51, v51, v66
	v_mul_f32_e32 v56, v36, v66
	v_mul_f32_e32 v57, v37, v66
	v_mul_f32_e32 v58, v38, v66
	v_mul_f32_e32 v39, v39, v66
	v_cvt_pk_bf16_f32 v36, v48, v49
	v_cvt_pk_bf16_f32 v37, v50, v51
	v_cvt_pk_bf16_f32 v38, v56, v57
	v_cvt_pk_bf16_f32 v39, v58, v39
	global_store_dwordx4 v[64:65], v[36:39], off offset:256
	s_nop 1
	v_fmamk_f32 v36, v169, 0x3a800000, v223
	v_rsq_f32_e32 v38, v36
	v_mad_i64_i32 v[36:37], s[0:1], v168, s89, v[156:157]
	v_lshl_add_u64 v[36:37], v[36:37], 0, v[158:159]
	v_mul_f32_e32 v28, v28, v38
	v_mul_f32_e32 v29, v29, v38
	v_mul_f32_e32 v30, v30, v38
	v_mul_f32_e32 v31, v31, v38
	v_mul_f32_e32 v39, v24, v38
	v_mul_f32_e32 v48, v25, v38
	v_mul_f32_e32 v49, v26, v38
	v_mul_f32_e32 v27, v27, v38
; #define PG8_BAR __builtin_amdgcn_s_barrier()
; template <class Epi, class Sched>
; __device__ __forceinline__ void gemm_phase(LAS unsigned char* lds, const Gemm g, const Sched& S, const Epi& E) {
;     ...
;         if (!has_next) break;
;         if (!epi_keep_acc(E, cur)) {
; #pragma unroll
;         for (int a = 0; a < 2; ++a)
; #pragma unroll
;             for (int b = 0; b < 2; ++b)
; #pragma unroll
;                 for (int m = 0; m < 4; ++m)
; #pragma unroll
;                     for (int n = 0; n < 2; ++n) acc[a][b][m][n] = (f32x4){0.f, 0.f, 0.f, 0.f};
;         }
;         cur = nxt; cA = nA; cB = nB; ++ui;
;         if (wr == 1) PG8_BAR;
;     __device__ __forceinline__ void operator()(AccT& acc, const Unit& u, int wr, int wc, int fr, int fq) const {
;         const bool gate = u.pn >= 5;
;         const int col0 = u.pn * 256 + wc * 32 + 8 * fq;
;         f32x4 gb[2][2];
; #pragma unroll
;         for (int bj = 0; bj < 2; ++bj)
; #pragma unroll
;             for (int n = 0; n < 2; ++n) gb[bj][n] = gate ? *(const f32x4*)(gbias + (col0 - 1280) + bj * 128 + 4 * n) : (f32x4){0.f, 0.f, 0.f, 0.f};
;         float rsv[2][4];
; #pragma unroll
;         for (int ai = 0; ai < 2; ++ai)
; #pragma unroll
;             for (int m = 0; m < 4; ++m) rsv[ai][m] = ssq[u.pm * 256 + ai * 128 + wr * 64 + m * 16 + fr];
; #pragma unroll
;         for (int ai = 0; ai < 2; ++ai)
; #pragma unroll
;             for (int m = 0; m < 4; ++m) {
;                 const int row = u.pm * 256 + ai * 128 + wr * 64 + m * 16 + fr;
;                 const float rs = __builtin_amdgcn_rsqf(rsv[ai][m] * (1.0f / 1024.0f) + EPS);
;                 bf16_t* rowp = P + (size_t)row * INW + col0;
; #pragma unroll
;                 for (int bj = 0; bj < 2; ++bj) {
;                     float v[8];
; #pragma unroll
;                     for (int n = 0; n < 2; ++n)
; #pragma unroll
;                         for (int j = 0; j < 4; ++j) {
;                             float x = acc[ai][bj][m][n][j] * rs;
;                             if (gate) { x += gb[bj][n][j]; x = __builtin_amdgcn_rcpf(1.0f + __builtin_amdgcn_exp2f(-LOG2E * x)); }
;                             v[n * 4 + j] = x;
;                         }
;                     *(u32x4*)(rowp + bj * 128) = pack8(v);
;                 }
;             }
;     }
	v_cvt_pk_bf16_f32 v24, v28, v29
	v_cvt_pk_bf16_f32 v25, v30, v31
	v_cvt_pk_bf16_f32 v26, v39, v48
	v_cvt_pk_bf16_f32 v27, v49, v27
	global_store_dwordx4 v[36:37], v[24:27], off
	s_nop 1
	v_mul_f32_e32 v20, v20, v38
	v_mul_f32_e32 v21, v21, v38
	v_mul_f32_e32 v22, v22, v38
	v_mul_f32_e32 v23, v23, v38
	v_mul_f32_e32 v24, v16, v38
	v_mul_f32_e32 v25, v17, v38
	v_mul_f32_e32 v26, v18, v38
	v_mul_f32_e32 v19, v19, v38
	v_cvt_pk_bf16_f32 v16, v20, v21
	v_cvt_pk_bf16_f32 v17, v22, v23
	v_cvt_pk_bf16_f32 v18, v24, v25
	v_cvt_pk_bf16_f32 v19, v26, v19
	global_store_dwordx4 v[36:37], v[16:19], off offset:256
	s_nop 1
	v_fmamk_f32 v16, v167, 0x3a800000, v223
	v_rsq_f32_e32 v18, v16
	v_mad_i64_i32 v[16:17], s[0:1], v166, s89, v[156:157]
	v_lshl_add_u64 v[16:17], v[16:17], 0, v[158:159]
	v_fmac_f32_e32 v52, v12, v18
	v_mul_f32_e32 v19, v12, v18
	v_mul_f32_e32 v12, 0xbfb8aa3b, v52
	v_exp_f32_e32 v12, v12
	v_fmac_f32_e32 v53, v13, v18
	v_fmac_f32_e32 v54, v14, v18
	v_fmac_f32_e32 v55, v15, v18
	v_add_f32_e32 v12, 1.0, v12
	v_rcp_f32_e32 v12, v12
	v_fmac_f32_e32 v44, v8, v18
	v_fmac_f32_e32 v45, v9, v18
	v_fmac_f32_e32 v46, v10, v18
	v_cndmask_b32_e64 v12, v19, v12, s[42:43]
	v_mul_f32_e32 v19, v13, v18
	v_mul_f32_e32 v13, 0xbfb8aa3b, v53
	v_exp_f32_e32 v13, v13
	v_fmac_f32_e32 v47, v11, v18
	v_fmac_f32_e32 v40, v4, v18
	v_fmac_f32_e32 v41, v5, v18
	v_add_f32_e32 v13, 1.0, v13
	v_rcp_f32_e32 v13, v13
	v_fmac_f32_e32 v42, v6, v18
	v_fmac_f32_e32 v43, v7, v18
	v_fmac_f32_e32 v32, v0, v18
	v_cndmask_b32_e64 v13, v19, v13, s[42:43]
	v_mul_f32_e32 v19, v14, v18
	v_mul_f32_e32 v14, 0xbfb8aa3b, v54
	v_exp_f32_e32 v14, v14
	v_fmac_f32_e32 v33, v1, v18
	v_fmac_f32_e32 v34, v2, v18
	v_fmac_f32_e32 v35, v3, v18
	v_add_f32_e32 v14, 1.0, v14
	v_rcp_f32_e32 v14, v14
	s_mov_b64 s[0:1], -1
	v_cndmask_b32_e64 v14, v19, v14, s[42:43]
	v_mul_f32_e32 v19, v15, v18
	v_mul_f32_e32 v15, 0xbfb8aa3b, v55
	v_exp_f32_e32 v15, v15
	s_nop 0
	v_add_f32_e32 v15, 1.0, v15
	v_rcp_f32_e32 v15, v15
	s_nop 0
	v_cndmask_b32_e64 v15, v19, v15, s[42:43]
	v_mul_f32_e32 v19, v8, v18
	v_mul_f32_e32 v8, 0xbfb8aa3b, v44
	v_exp_f32_e32 v8, v8
	s_nop 0
	v_add_f32_e32 v8, 1.0, v8
	v_rcp_f32_e32 v8, v8
	s_nop 0
	v_cndmask_b32_e64 v19, v19, v8, s[42:43]
	v_mul_f32_e32 v8, v9, v18
	v_mul_f32_e32 v9, 0xbfb8aa3b, v45
	v_exp_f32_e32 v9, v9
	s_nop 0
	v_add_f32_e32 v9, 1.0, v9
	v_rcp_f32_e32 v9, v9
	s_nop 0
	v_cndmask_b32_e64 v20, v8, v9, s[42:43]
	v_mul_f32_e32 v9, 0xbfb8aa3b, v46
	v_exp_f32_e32 v9, v9
	v_mul_f32_e32 v8, v10, v18
	v_add_f32_e32 v9, 1.0, v9
	v_rcp_f32_e32 v9, v9
	s_nop 0
	v_cndmask_b32_e64 v21, v8, v9, s[42:43]
	v_mul_f32_e32 v9, 0xbfb8aa3b, v47
	v_exp_f32_e32 v9, v9
	v_mul_f32_e32 v8, v11, v18
	v_add_f32_e32 v9, 1.0, v9
	v_rcp_f32_e32 v9, v9
	s_nop 0
	v_cndmask_b32_e64 v11, v8, v9, s[42:43]
	v_cvt_pk_bf16_f32 v8, v12, v13
	v_cvt_pk_bf16_f32 v9, v14, v15
	v_cvt_pk_bf16_f32 v10, v19, v20
	v_cvt_pk_bf16_f32 v11, v21, v11
	global_store_dwordx4 v[16:17], v[8:11], off
	s_nop 1
	v_mul_f32_e32 v8, v4, v18
	v_mul_f32_e32 v4, 0xbfb8aa3b, v40
	v_exp_f32_e32 v4, v4
	s_nop 0
	v_add_f32_e32 v4, 1.0, v4
	v_rcp_f32_e32 v4, v4
	s_nop 0
	v_cndmask_b32_e64 v4, v8, v4, s[42:43]
	v_mul_f32_e32 v8, v5, v18
	v_mul_f32_e32 v5, 0xbfb8aa3b, v41
	v_exp_f32_e32 v5, v5
	s_nop 0
	v_add_f32_e32 v5, 1.0, v5
	v_rcp_f32_e32 v5, v5
	s_nop 0
	v_cndmask_b32_e64 v5, v8, v5, s[42:43]
	v_mul_f32_e32 v8, v6, v18
	v_mul_f32_e32 v6, 0xbfb8aa3b, v42
	v_exp_f32_e32 v6, v6
	s_nop 0
	v_add_f32_e32 v6, 1.0, v6
	v_rcp_f32_e32 v6, v6
	s_nop 0
	v_cndmask_b32_e64 v6, v8, v6, s[42:43]
	v_mul_f32_e32 v8, v7, v18
	v_mul_f32_e32 v7, 0xbfb8aa3b, v43
	v_exp_f32_e32 v7, v7
	s_nop 0
	v_add_f32_e32 v7, 1.0, v7
	v_rcp_f32_e32 v7, v7
	s_nop 0
	v_cndmask_b32_e64 v7, v8, v7, s[42:43]
	v_mul_f32_e32 v8, v0, v18
	v_mul_f32_e32 v0, 0xbfb8aa3b, v32
	v_exp_f32_e32 v0, v0
	s_nop 0
	v_add_f32_e32 v0, 1.0, v0
	v_rcp_f32_e32 v0, v0
	s_nop 0
	v_cndmask_b32_e64 v8, v8, v0, s[42:43]
	v_mul_f32_e32 v0, v1, v18
	v_mul_f32_e32 v1, 0xbfb8aa3b, v33
	v_exp_f32_e32 v1, v1
	s_nop 0
	v_add_f32_e32 v1, 1.0, v1
	v_rcp_f32_e32 v1, v1
	s_nop 0
	v_cndmask_b32_e64 v9, v0, v1, s[42:43]
	v_mul_f32_e32 v1, 0xbfb8aa3b, v34
	v_exp_f32_e32 v1, v1
	v_mul_f32_e32 v0, v2, v18
	v_add_f32_e32 v1, 1.0, v1
	v_rcp_f32_e32 v1, v1
	s_nop 0
	v_cndmask_b32_e64 v10, v0, v1, s[42:43]
	v_mul_f32_e32 v1, 0xbfb8aa3b, v35
	v_exp_f32_e32 v1, v1
	v_mul_f32_e32 v0, v3, v18
	v_add_f32_e32 v1, 1.0, v1
	v_rcp_f32_e32 v1, v1
	s_nop 0
	v_cndmask_b32_e64 v3, v0, v1, s[42:43]
	v_cvt_pk_bf16_f32 v0, v4, v5
	v_cvt_pk_bf16_f32 v1, v6, v7
	v_cvt_pk_bf16_f32 v2, v8, v9
	v_cvt_pk_bf16_f32 v3, v10, v3
	global_store_dwordx4 v[16:17], v[0:3], off offset:256
.Lmy_p1_join:
	s_cbranch_vccnz .LBB0_170
	s_andn2_b64 vcc, exec, s[8:9]
	s_cbranch_vccnz .LBB0_169
	s_barrier
	s_branch .LBB0_169
